# grid barrier: followers poll the top-level generation word directly (one release hop removed), unused per-XCD generation add dropped
# baseline (speedup 1.0000x reference)
.LBB0_641:
	s_or_b64 exec, exec, s[22:23]
	v_cvt_f32_u32_e32 v4, v2
	s_waitcnt vmcnt(0)
	v_readfirstlane_b32 s2, v3
	v_sub_u32_e32 v3, 0, v2
	v_rcp_iflag_f32_e32 v4, v4
	v_add_u32_e32 v5, s2, v1
	v_mul_f32_e32 v4, 0x4f7ffffe, v4
	v_cvt_u32_f32_e32 v4, v4
	v_mul_lo_u32 v1, v3, v4
	v_mul_hi_u32 v1, v4, v1
	v_add_u32_e32 v1, v4, v1
	v_mul_hi_u32 v1, v5, v1
	v_mul_lo_u32 v3, v1, v2
	v_sub_u32_e32 v3, v5, v3
	v_add_u32_e32 v4, 1, v1
	v_cmp_ge_u32_e32 vcc, v3, v2
	s_nop 1
	v_cndmask_b32_e32 v1, v1, v4, vcc
	v_sub_u32_e32 v4, v3, v2
	v_cndmask_b32_e32 v3, v3, v4, vcc
	v_add_u32_e32 v4, 1, v1
	v_cmp_ge_u32_e32 vcc, v3, v2
	v_add_u32_e32 v3, 1, v5
	s_nop 0
	v_cndmask_b32_e32 v1, v1, v4, vcc
	v_mul_lo_u32 v4, v2, v1
	v_add_u32_e32 v2, v4, v2
	v_cmp_ne_u32_e32 vcc, v3, v2
	s_and_saveexec_b64 s[22:23], vcc
	s_xor_b64 s[22:23], exec, s[22:23]
	s_cbranch_execz .LBB0_655
	v_readlane_b32 s4, v255, 13
	v_readlane_b32 s5, v255, 14
	s_waitcnt lgkmcnt(0)
	s_nop 3
	global_load_dword v0, v185, s[4:5] sc1
	s_waitcnt vmcnt(0)
	v_cmp_eq_u32_e32 vcc, v0, v1
	s_and_saveexec_b64 s[28:29], vcc
	s_cbranch_execz .LBB0_654
	s_mov_b32 s2, 1
	s_mov_b64 s[30:31], 0
	s_branch .LBB0_645

.LBB0_649:
	v_readlane_b32 s4, v255, 13
	v_readlane_b32 s5, v255, 14
	s_add_i32 s2, s2, 1
	s_mov_b64 s[38:39], -1
	s_nop 2
	global_load_dword v0, v185, s[4:5] sc1
	s_waitcnt vmcnt(0)
	v_cmp_ne_u32_e32 vcc, v0, v1
	s_orn2_b64 s[36:37], vcc, exec
	s_branch .LBB0_644

.LBB0_672:
	s_or_b64 exec, exec, s[22:23]
	s_mov_b64 s[22:23], exec
	v_mbcnt_lo_u32_b32 v0, s22, 0
	v_mbcnt_hi_u32_b32 v0, s23, v0
	v_cmp_eq_u32_e32 vcc, 0, v0
	s_waitcnt vmcnt(0)
	buffer_inv sc1
	s_and_saveexec_b64 s[28:29], vcc
	s_cbranch_execz .LBB0_21
	s_bcnt1_i32_b64 s2, s[22:23]
	s_branch .LBB0_21
